# compressed-block phase: static priority raise for the four waves that hold the late (long) query block
# baseline (speedup 1.0000x reference)
; __device__ __forceinline__ int make_tid(int wave0) { int t = wave0 * 64 + (int)__builtin_amdgcn_mbcnt_hi(~0u, __builtin_amdgcn_mbcnt_lo(~0u, 0u)); asm volatile("" : "+v"(t)); return t; }
; __device__ __forceinline__ int opaque_bid() { int b = blockIdx.x; asm volatile("" : "+s"(b)); return b; }
; #define LAS __attribute__((address_space(3)))
; __device__ __forceinline__ void cmp_phase(LAS unsigned char* lds, const bf16_t* __restrict__ P, const bf16_t* __restrict__ Kc, const bf16_t* __restrict__ Vc,
;                                           bf16_t* __restrict__ ocmp, unsigned long long* __restrict__ mask, int G, const int wave0) {
;     ...
;     for (int unit = opaque_bid(); unit < 256; unit += G) {
;         const int tid = make_tid(wave0), lane = tid & 63, r32 = lane & 31, hi = lane >> 5;
;         const int b = unit >> 5, g = (unit >> 4) & 1, kq = (unit >> 1) & 7, hq = unit & 1, bg = b * 2 + g;
;         const int qb = (wid < 4) ? (15 - kq) : kq;
;         __syncthreads();
; #pragma unroll
;         for (int i = 0; i < 4; ++i) {
;             const int c = tid + 512 * i, row = c >> 3, ch = c & 7;
;             const u32x4 kv = *(const u32x4*)(Kc + (size_t)(bg * 256 + row) * 64 + ch * 8);
;             const u32x4 vv = *(const u32x4*)(Vc + (size_t)(bg * 256 + row) * 64 + ch * 8);
;             *(LAS u32x4*)(lds + row * KSTR + ch * 16) = kv;
;             *(LAS u32x4*)(lds + VOFFC + (ch >> 2) * 16384 + row * 64 + (ch & 3) * 16) = vv;
;         }
;         __syncthreads();
;         const int tw0 = qb * 256 + hq * 128 + 32 * (wid & 3), tq = tw0 + r32;
;         const int nch = ((tw0 >> 4) >> 6) + 1;
;         const size_t row = (size_t)b * SEQ + tq;
;         LAS float* mi = (LAS float*)(lds + MI_OFF + wid * 1024);
;         LAS float* sc = (LAS float*)(lds + SC_OFF + wid * (32 * 65 * 4) + r32 * (65 * 4));
;     ...
;         for (int hh = 0; hh < 4; ++hh) {
;             const int head = 4 * g + hh;
;             bf16x8 qf[4];
; #pragma unroll
;             for (int ds = 0; ds < 4; ++ds) qf[ds] = *(const bf16x8*)(P + row * NPJ + C_NQ + head * 64 + 16 * ds + 8 * hi);
.LBB0_761:
	s_ashr_i32 s4, s3, 5
	s_bfe_u32 s6, s3, 0x10004
	s_lshl_b32 s2, s4, 1
	s_or_b32 s8, s2, s6
	s_mov_b32 s2, s8
	v_mov_b32_e32 v96, v246
	v_writelane_b32 v255, s2, 5
	s_waitcnt vmcnt(0)
	v_lshlrev_b32_e32 v40, 4, v96
	v_writelane_b32 v255, s3, 6
	s_lshl_b32 s2, s8, 8
	v_readlane_b32 s8, v254, 56
	v_add_u32_e32 v8, 0x200, v96
	v_add_u32_e32 v16, 0x400, v96
	s_waitcnt lgkmcnt(1)
	v_add_u32_e32 v28, 0x600, v96
	v_and_b32_e32 v214, 0x70, v40
	v_readlane_b32 s9, v254, 57
	v_ashrrev_i32_e32 v33, 3, v96
	v_ashrrev_i32_e32 v38, 3, v8
	v_ashrrev_i32_e32 v41, 3, v16
	v_ashrrev_i32_e32 v42, 3, v28
	v_lshl_add_u64 v[24:25], s[8:9], 0, v[214:215]
	v_readlane_b32 s8, v254, 58
	v_add_u32_e32 v0, s2, v33
	v_add_u32_e32 v8, s2, v38
	v_add_u32_e32 v16, s2, v41
	v_add_u32_e32 v28, s2, v42
	v_readlane_b32 s9, v254, 59
	v_ashrrev_i32_e32 v1, 31, v0
	v_ashrrev_i32_e32 v9, 31, v8
	v_ashrrev_i32_e32 v17, 31, v16
	v_ashrrev_i32_e32 v29, 31, v28
	v_lshl_add_u64 v[26:27], s[8:9], 0, v[214:215]
	v_lshlrev_b64 v[0:1], 7, v[0:1]
	v_lshlrev_b64 v[8:9], 7, v[8:9]
	v_lshlrev_b64 v[16:17], 7, v[16:17]
	v_lshlrev_b64 v[28:29], 7, v[28:29]
	v_lshl_add_u64 v[2:3], v[24:25], 0, v[0:1]
	v_lshl_add_u64 v[4:5], v[26:27], 0, v[0:1]
	v_lshl_add_u64 v[10:11], v[24:25], 0, v[8:9]
	v_lshl_add_u64 v[12:13], v[26:27], 0, v[8:9]
	v_lshl_add_u64 v[18:19], v[24:25], 0, v[16:17]
	v_lshl_add_u64 v[20:21], v[26:27], 0, v[16:17]
	v_lshl_add_u64 v[24:25], v[24:25], 0, v[28:29]
	v_lshl_add_u64 v[28:29], v[26:27], 0, v[28:29]
	s_barrier
	global_load_dwordx4 v[0:3], v[2:3], off
	s_nop 0
	global_load_dwordx4 v[4:7], v[4:5], off
	s_nop 0
	global_load_dwordx4 v[8:11], v[10:11], off
	s_nop 0
	global_load_dwordx4 v[12:15], v[12:13], off
	s_nop 0
	global_load_dwordx4 v[16:19], v[18:19], off
	s_nop 0
	global_load_dwordx4 v[20:23], v[20:21], off
	s_nop 0
	global_load_dwordx4 v[24:27], v[24:25], off
	s_waitcnt lgkmcnt(0)
	global_load_dwordx4 v[28:31], v[28:29], off
	s_lshl_b32 s5, s3, 7
	v_lshlrev_b32_e32 v32, 12, v96
	s_and_b32 s7, s5, 0x700
	v_and_b32_e32 v34, 0x4000, v32
	v_and_b32_e32 v35, 48, v40
	v_add_u32_e32 v32, 0, v214
	s_lshr_b32 s8, s3, 4
	v_writelane_b32 v255, s3, 7
	s_xor_b32 s9, s7, 0xf00
	v_add3_u32 v44, 0, v34, v35
	v_mad_u64_u32 v[34:35], s[2:3], v33, s84, v[32:33]
	v_mad_u64_u32 v[36:37], s[2:3], v38, s84, v[32:33]
	s_and_b64 s[2:3], s[66:67], exec
	v_lshl_add_u32 v35, v33, 6, v44
	v_lshl_add_u32 v37, v38, 6, v44
	v_mad_u64_u32 v[38:39], s[2:3], v41, s84, v[32:33]
	v_mad_u64_u32 v[32:33], s[2:3], v42, s84, v[32:33]
	s_cselect_b32 s7, s9, s7
	s_cbranch_scc0 .Lcp_np
	s_setprio 2
.Lcp_np:
	s_and_b32 s2, s5, 0x80
	v_readlane_b32 s3, v253, 13
	s_or_b32 s2, s3, s2
	v_and_b32_e32 v81, 31, v96
	s_or_b32 s87, s2, s7
	s_ashr_i32 s5, s4, 31
	v_readlane_b32 s10, v254, 48
	v_or_b32_e32 v82, s87, v81
	s_lshl_b64 s[2:3], s[4:5], 12
	v_readlane_b32 s11, v254, 49
	v_lshl_add_u32 v39, v41, 6, v44
	v_lshl_add_u32 v33, v42, 6, v44
	v_bfe_u32 v80, v96, 5, 1
	v_lshlrev_b32_e32 v84, 4, v80
	v_mov_b32_e32 v85, v215
	v_and_b32_e32 v43, 63, v96
	v_mad_u32_u24 v99, v81, s84, v84
	s_waitcnt vmcnt(7)
	ds_write_b128 v34, v[0:3]
	s_waitcnt vmcnt(6)
	ds_write_b128 v35, v[4:7] offset:36864
	s_waitcnt vmcnt(5)
	ds_write_b128 v36, v[8:11]
	s_waitcnt vmcnt(4)
	ds_write_b128 v37, v[12:15] offset:36864
	s_waitcnt vmcnt(3)
	ds_write_b128 v38, v[16:19]
	s_waitcnt vmcnt(2)
	ds_write_b128 v39, v[20:23] offset:36864
	s_waitcnt vmcnt(1)
	ds_write_b128 v32, v[24:27]
	s_waitcnt vmcnt(0)
	ds_write_b128 v33, v[28:31] offset:36864
	v_or_b32_e32 v0, s2, v82
	v_mov_b64_e32 v[2:3], s[10:11]
	v_mad_u64_u32 v[2:3], s[10:11], v0, s65, v[2:3]
	v_mov_b32_e32 v4, 0x1400
	v_mad_i32_i24 v3, s3, v4, v3
	v_lshl_add_u64 v[86:87], v[2:3], 0, v[84:85]
	v_lshlrev_b32_e32 v85, 3, v81
	v_readlane_b32 s2, v253, 6
	v_mov_b32_e32 v1, s3
	v_lshlrev_b64 v[0:1], 10, v[0:1]
	v_add_u32_e32 v98, s2, v85
	v_readlane_b32 s2, v254, 60
	v_readlane_b32 s3, v254, 61
	v_lshlrev_b32_e32 v2, 1, v96
	v_lshlrev_b32_e32 v3, 3, v96
	v_and_b32_e32 v5, 0xc0, v40
	v_lshl_add_u64 v[88:89], s[2:3], 0, v[0:1]
	v_cmp_gt_u32_e64 s[2:3], 32, v43
	v_lshlrev_b32_e32 v4, 3, v80
	v_and_b32_e32 v2, 32, v2
	v_and_b32_e32 v3, 24, v3
	v_cndmask_b32_e64 v0, 24, 16, s[2:3]
	s_and_b32 s11, s7, 0xc00
	v_lshl_or_b32 v1, v80, 8, v5
	s_lshr_b32 s86, s7, 10
	s_add_i32 s5, s87, 0xfffffbf1
	v_lshlrev_b32_e32 v83, 6, v80
	v_subrev_u32_e32 v97, 31, v82
	s_mov_b32 s9, 0
	s_lshl_b32 s10, s6, 8
	v_writelane_b32 v255, s7, 9
	s_addk_i32 s11, 0x400
	v_add_u32_e32 v100, 0, v99
	v_or3_b32 v101, v1, v2, v3
	v_lshlrev_b32_e32 v214, 1, v4
	v_lshlrev_b32_e32 v90, 1, v0
	s_mov_b32 s80, s10
	v_lshl_add_u64 v[166:167], s[80:81], 1, v[86:87]
	global_load_dwordx4 v[130:133], v[166:167], off offset:2752
	global_load_dwordx4 v[134:137], v[166:167], off offset:2784
	global_load_dwordx4 v[138:141], v[166:167], off offset:2816
	global_load_dwordx4 v[142:145], v[166:167], off offset:2848
	global_load_dwordx4 v[146:149], v[166:167], off offset:2368
	global_load_dwordx4 v[150:153], v[166:167], off offset:2400
	global_load_dwordx4 v[154:157], v[166:167], off offset:2432
	global_load_dwordx4 v[158:161], v[166:167], off offset:2464
	global_load_dwordx4 v[200:203], v[166:167], off offset:2496
	global_load_dwordx4 v[204:207], v[166:167], off offset:2528
	global_load_dwordx4 v[208:211], v[166:167], off offset:2560
	global_load_dwordx4 v[216:219], v[166:167], off offset:2592
	global_load_dwordx4 v[220:223], v[166:167], off offset:2624
	global_load_dwordx4 v[224:227], v[166:167], off offset:2656
	global_load_dwordx4 v[228:231], v[166:167], off offset:2688
	global_load_dwordx4 v[232:235], v[166:167], off offset:2720
	s_waitcnt lgkmcnt(0)
	s_barrier
	s_waitcnt vmcnt(0)
	s_branch .LBB0_763

; __device__ __forceinline__ unsigned or32x(unsigned v) { auto rr = __builtin_amdgcn_permlane32_swap(v, v, false, false); return rr[0] | rr[1]; }
; __device__ __forceinline__ void cmp_phase(LAS unsigned char* lds, const bf16_t* __restrict__ P, const bf16_t* __restrict__ Kc, const bf16_t* __restrict__ Vc,
;                                           bf16_t* __restrict__ ocmp, unsigned long long* __restrict__ mask, int G, const int wave0) {
;     ...
;             unsigned mlo = 0u, mhi = 0u;
; #pragma unroll
;             for (int i = 0; i < 32; ++i) {
;                 const unsigned bit = (rank[i] < 16) ? 1u : 0u;
;                 if (i < 16) mlo |= bit << (2 * i + hi); else mhi |= bit << (2 * (i - 16) + hi);
;             }
;             mlo = or32x(mlo); mhi = or32x(mhi);
;             if (hi == 0) mask[(size_t)bg * SEQ + tq] = ((unsigned long long)mhi << 32) | (unsigned long long)mlo;
.LBB0_921:
	s_setprio 0
	v_cmp_gt_u32_e32 vcc, 16, v97
	s_waitcnt lgkmcnt(14)
	v_or_b32_e32 v2, 2, v80
	v_or_b32_e32 v3, 4, v80
	v_cndmask_b32_e64 v0, 0, 1, vcc
	v_cmp_gt_u32_e32 vcc, 16, v96
	v_lshlrev_b32_e32 v0, v80, v0
	s_waitcnt lgkmcnt(13)
	v_or_b32_e32 v4, 6, v80
	v_cndmask_b32_e64 v1, 0, 1, vcc
	v_cmp_gt_u32_e32 vcc, 16, v95
	v_lshl_or_b32 v0, v1, v2, v0
	v_or_b32_e32 v5, 8, v80
	v_cndmask_b32_e64 v1, 0, 1, vcc
	v_cmp_gt_u32_e32 vcc, 16, v94
	v_lshl_or_b32 v0, v1, v3, v0
	s_waitcnt lgkmcnt(12)
	v_or_b32_e32 v7, 10, v80
	v_cndmask_b32_e64 v1, 0, 1, vcc
	v_cmp_gt_u32_e32 vcc, 16, v93
	v_lshl_or_b32 v0, v1, v4, v0
	s_waitcnt lgkmcnt(11)
	v_or_b32_e32 v9, 14, v80
	v_cndmask_b32_e64 v1, 0, 1, vcc
	v_cmp_gt_u32_e32 vcc, 16, v92
	v_lshlrev_b32_e32 v1, v5, v1
	s_waitcnt lgkmcnt(10)
	v_or_b32_e32 v11, 18, v80
	v_cndmask_b32_e64 v6, 0, 1, vcc
	v_lshlrev_b32_e32 v6, v7, v6
	v_cmp_gt_u32_e32 vcc, 16, v91
	v_or3_b32 v0, v1, v0, v6
	v_or_b32_e32 v6, 12, v80
	v_cndmask_b32_e64 v1, 0, 1, vcc
	v_cmp_gt_u32_e32 vcc, 16, v90
	v_lshlrev_b32_e32 v1, v6, v1
	s_waitcnt lgkmcnt(9)
	v_or_b32_e32 v13, 22, v80
	v_cndmask_b32_e64 v8, 0, 1, vcc
	v_lshlrev_b32_e32 v8, v9, v8
	v_cmp_gt_u32_e32 vcc, 16, v89
	v_or3_b32 v0, v0, v1, v8
	v_or_b32_e32 v8, 16, v80
	v_cndmask_b32_e64 v1, 0, 1, vcc
	v_cmp_gt_u32_e32 vcc, 16, v88
	v_lshlrev_b32_e32 v1, v8, v1
	s_waitcnt lgkmcnt(8)
	v_or_b32_e32 v15, 26, v80
	v_cndmask_b32_e64 v10, 0, 1, vcc
	v_lshlrev_b32_e32 v10, v11, v10
	v_cmp_gt_u32_e32 vcc, 16, v87
	v_or3_b32 v0, v0, v1, v10
	v_or_b32_e32 v10, 20, v80
	v_cndmask_b32_e64 v1, 0, 1, vcc
	v_cmp_gt_u32_e32 vcc, 16, v86
	v_lshlrev_b32_e32 v1, v10, v1
	s_waitcnt lgkmcnt(7)
	v_or_b32_e32 v17, 30, v80
	v_cndmask_b32_e64 v12, 0, 1, vcc
	v_lshlrev_b32_e32 v12, v13, v12
	v_cmp_gt_u32_e32 vcc, 16, v85
	v_or3_b32 v0, v0, v1, v12
	v_or_b32_e32 v12, 24, v80
	v_cndmask_b32_e64 v1, 0, 1, vcc
	v_cmp_gt_u32_e32 vcc, 16, v84
	v_lshlrev_b32_e32 v1, v12, v1
	s_nop 0
	v_cndmask_b32_e64 v14, 0, 1, vcc
	v_lshlrev_b32_e32 v14, v15, v14
	v_cmp_gt_u32_e32 vcc, 16, v83
	v_or3_b32 v0, v0, v1, v14
	v_or_b32_e32 v14, 28, v80
	v_cndmask_b32_e64 v1, 0, 1, vcc
	v_cmp_gt_u32_e32 vcc, 16, v81
	v_lshlrev_b32_e32 v1, v14, v1
	s_nop 0
	v_cndmask_b32_e64 v16, 0, 1, vcc
	v_lshlrev_b32_e32 v16, v17, v16
	v_cmp_gt_u32_e32 vcc, 16, v79
	v_or3_b32 v0, v0, v1, v16
	s_nop 0
	v_cndmask_b32_e64 v1, 0, 1, vcc
	v_cmp_gt_u32_e32 vcc, 16, v78
	v_lshlrev_b32_e32 v1, v80, v1
	s_nop 0
	v_cndmask_b32_e64 v16, 0, 1, vcc
	v_cmp_gt_u32_e32 vcc, 16, v77
	v_lshl_or_b32 v1, v16, v2, v1
	s_nop 0
	v_cndmask_b32_e64 v2, 0, 1, vcc
	v_cmp_gt_u32_e32 vcc, 16, v76
	v_lshl_or_b32 v1, v2, v3, v1
	s_nop 0
	v_cndmask_b32_e64 v2, 0, 1, vcc
	v_cmp_gt_u32_e32 vcc, 16, v75
	v_lshl_or_b32 v1, v2, v4, v1
	s_nop 0
	v_cndmask_b32_e64 v2, 0, 1, vcc
	v_cmp_gt_u32_e32 vcc, 16, v74
	v_lshlrev_b32_e32 v2, v5, v2
	s_nop 0
	v_cndmask_b32_e64 v3, 0, 1, vcc
	v_lshlrev_b32_e32 v3, v7, v3
	v_cmp_gt_u32_e32 vcc, 16, v73
	v_or3_b32 v1, v2, v1, v3
	s_nop 0
	v_cndmask_b32_e64 v2, 0, 1, vcc
	v_cmp_gt_u32_e32 vcc, 16, v72
	v_lshlrev_b32_e32 v2, v6, v2
	s_nop 0
	v_cndmask_b32_e64 v3, 0, 1, vcc
	v_lshlrev_b32_e32 v3, v9, v3
	v_cmp_gt_u32_e32 vcc, 16, v71
	v_or3_b32 v1, v1, v2, v3
	s_nop 0
	v_cndmask_b32_e64 v2, 0, 1, vcc
	v_cmp_gt_u32_e32 vcc, 16, v70
	v_lshlrev_b32_e32 v2, v8, v2
	s_nop 0
	v_cndmask_b32_e64 v3, 0, 1, vcc
	v_lshlrev_b32_e32 v3, v11, v3
	v_cmp_gt_u32_e32 vcc, 16, v69
	v_or3_b32 v1, v1, v2, v3
	s_nop 0
	v_cndmask_b32_e64 v2, 0, 1, vcc
	v_cmp_gt_u32_e32 vcc, 16, v68
	v_lshlrev_b32_e32 v2, v10, v2
	s_nop 0
	v_cndmask_b32_e64 v3, 0, 1, vcc
	v_lshlrev_b32_e32 v3, v13, v3
	v_cmp_gt_u32_e32 vcc, 16, v67
	v_or3_b32 v1, v1, v2, v3
	s_nop 0
	v_cndmask_b32_e64 v2, 0, 1, vcc
	v_cmp_gt_u32_e32 vcc, 16, v66
	v_lshlrev_b32_e32 v2, v12, v2
	s_nop 0
	v_cndmask_b32_e64 v3, 0, 1, vcc
	v_lshlrev_b32_e32 v3, v15, v3
	v_cmp_gt_u32_e32 vcc, 16, v65
	v_or3_b32 v1, v1, v2, v3
	s_nop 0
	v_cndmask_b32_e64 v2, 0, 1, vcc
	v_cmp_gt_u32_e32 vcc, 16, v64
	v_lshlrev_b32_e32 v2, v14, v2
	s_nop 0
	v_cndmask_b32_e64 v3, 0, 1, vcc
	v_lshlrev_b32_e32 v3, v17, v3
	v_or3_b32 v1, v1, v2, v3
	v_mov_b32_e32 v2, v0
	v_mov_b32_e32 v3, v1
	s_nop 0
	v_permlane32_swap_b32_e32 v0, v2
	v_permlane32_swap_b32_e32 v1, v3
	s_and_saveexec_b64 s[4:5], s[2:3]
	v_readlane_b32 s8, v254, 50
	v_readlane_b32 s9, v254, 51
	s_cbranch_execz .LBB0_760
	v_readlane_b32 s2, v255, 5
	v_readlane_b32 s3, v255, 6
	s_ashr_i32 s3, s2, 31
	s_lshl_b64 s[2:3], s[2:3], 15
	v_readlane_b32 s6, v254, 62
	s_add_u32 s2, s6, s2
	v_readlane_b32 s6, v254, 63
	s_addc_u32 s3, s6, s3
	v_lshlrev_b32_e32 v4, 3, v82
	v_or_b32_e32 v1, v1, v3
	v_or_b32_e32 v0, v0, v2
	global_store_dwordx2 v4, v[0:1], s[2:3]
	s_branch .LBB0_760
